# version 63 plus: sample-row GEMM loads two iterations ahead, all plain packed f32 VALU ops split into single ops (bit-identical), every MFMA block 8-byte aligned
# baseline (speedup 1.0000x reference)
; __device__ __forceinline__ unsigned cvt_pk_bf16(float lo, float hi) { unsigned r; asm volatile("v_cvt_pk_bf16_f32 %0, %1, %2" : "=v"(r) : "v"(lo), "v"(hi)); return r; }
; __device__ __forceinline__ float silu_f(float x) { return x * __builtin_amdgcn_rcpf(1.0f + __expf(-x)); }
; __device__ __forceinline__ float silu_f(float x) { return x * __builtin_amdgcn_rcpf(1.0f + __expf(-x)); }
;     __device__ __forceinline__ void operator()(const f32x4 (&acc)[2][2][4][2], const Unit& u, int wr, int wc, int fr, int fq) const {
;     ...
;             for (int m = 0; m < 4; ++m) rs[ai][m] = rowss[row0 + ai * HALF + m * 16];
; #pragma unroll
;         for (int ai = 0; ai < 2; ++ai)
; #pragma unroll
;             for (int m = 0; m < 4; ++m) {
;                 const int row = row0 + ai * HALF + m * 16;
;                 const float r = rsqrtf(rs[ai][m] * (1.0f / 1024.0f) + RMS_EPS);
; #pragma unroll
;                 for (int bj = 0; bj < 2; ++bj) {
;                     f32x4 a = acc[ai][bj][m][0] * r, b = acc[ai][bj][m][1] * r;
;                     if (act) {
; #pragma unroll
;                         for (int e = 0; e < 4; ++e) { a[e] = silu_f(a[e]); b[e] = silu_f(b[e]); }
;                     }
;                     u32x4 w; w.x = cvt_pk_bf16(a[0], a[1]); w.y = cvt_pk_bf16(a[2], a[3]); w.z = cvt_pk_bf16(b[0], b[1]); w.w = cvt_pk_bf16(b[2], b[3]);
;                     *(u32x4*)(P + (size_t)row * ldp + col0 + bj * HALF) = w;
;                 }
.LBB0_96:
	v_lshl_add_u32 v144, s38, 8, v5
	v_ashrrev_i32_e32 v145, 31, v144
	v_lshl_add_u64 v[146:147], v[144:145], 2, s[6:7]
	s_add_i32 s11, s10, -3
	s_and_b32 s11, s11, -6
	s_cmp_eq_u32 s11, 0
	s_cselect_b64 s[12:13], -1, 0
	s_cmp_lg_u32 s11, 0
	s_mov_b32 s11, 0x800000
	s_waitcnt vmcnt(0)
	v_fmamk_f32 v146, v226, 0x3a800000, v231
	v_cmp_gt_f32_e32 vcc, s11, v146
	v_mul_f32_e32 v147, 0x4b800000, v146
	s_nop 0
	v_cndmask_b32_e32 v146, v146, v147, vcc
	v_rsq_f32_e32 v146, v146
	s_nop 0
	v_mul_f32_e32 v147, 0x45800000, v146
	v_cndmask_b32_e32 v146, v146, v147, vcc
	v_mul_f32_e32 v132, v132, v146
	v_mul_f32_e32 v133, v133, v146
	v_mul_f32_e32 v130, v130, v146
	v_mul_f32_e32 v131, v131, v146
	v_mul_f32_e32 v128, v128, v146
	v_mul_f32_e32 v129, v129, v146
	v_mul_f32_e32 v148, v126, v146
	v_mul_f32_e32 v149, v127, v146
	s_cbranch_scc1 .LBB0_98
	v_mul_f32_e32 v147, 0xbfb8aa3b, v149
	v_exp_f32_e32 v147, v147
	v_mul_f32_e32 v127, 0xbfb8aa3b, v148
	v_exp_f32_e32 v127, v127
	v_mul_f32_e32 v126, 0xbfb8aa3b, v130
	v_add_f32_e32 v147, 1.0, v147
	v_rcp_f32_e32 v161, v147
	v_mul_f32_e32 v147, 0xbfb8aa3b, v132
	v_add_f32_e32 v127, 1.0, v127
	v_exp_f32_e32 v147, v147
	v_rcp_f32_e32 v160, v127
	v_mul_f32_e32 v127, 0xbfb8aa3b, v131
	v_exp_f32_e32 v126, v126
	v_exp_f32_e32 v127, v127
	v_add_f32_e32 v147, 1.0, v147
	v_rcp_f32_e32 v162, v147
	v_mul_f32_e32 v147, 0xbfb8aa3b, v128
	v_add_f32_e32 v126, 1.0, v126
	v_add_f32_e32 v127, 1.0, v127
	v_exp_f32_e32 v147, v147
	v_rcp_f32_e32 v126, v126
	v_rcp_f32_e32 v127, v127
	v_mul_f32_e32 v148, v148, v160
	v_mul_f32_e32 v149, v149, v161
	v_add_f32_e32 v147, 1.0, v147
	v_rcp_f32_e32 v164, v147
	v_mul_f32_e32 v147, 0xbfb8aa3b, v133
	v_mul_f32_e32 v130, v130, v126
	v_mul_f32_e32 v131, v131, v127
	v_mul_f32_e32 v126, 0xbfb8aa3b, v129
	v_exp_f32_e32 v147, v147
	v_exp_f32_e32 v126, v126
	v_add_f32_e32 v147, 1.0, v147
	v_add_f32_e32 v126, 1.0, v126
	v_rcp_f32_e32 v163, v147
	v_rcp_f32_e32 v165, v126
	v_mul_f32_e32 v132, v132, v162
	v_mul_f32_e32 v133, v133, v163
	v_mul_f32_e32 v128, v128, v164
	v_mul_f32_e32 v129, v129, v165
.LBB0_98:
	v_lshl_or_b32 v126, s10, 8, v151
	v_cvt_pk_bf16_f32 v130, v130, v131
	v_cvt_pk_bf16_f32 v131, v132, v133
	v_cvt_pk_bf16_f32 v132, v148, v149
	v_cvt_pk_bf16_f32 v133, v128, v129
	v_mov_b64_e32 v[128:129], s[86:87]
	v_ashrrev_i32_e32 v127, 31, v126
	v_mad_i64_i32 v[128:129], s[10:11], v144, s55, v[128:129]
	v_lshl_add_u64 v[128:129], v[126:127], 1, v[128:129]
	global_store_dwordx4 v[128:129], v[130:133], off
	v_mov_b32_e32 v147, v146
	v_mul_f32_e32 v122, v122, v146
	v_mul_f32_e32 v123, v123, v147
	v_mov_b32_e32 v130, v146
	v_mov_b32_e32 v131, v146
	v_mul_f32_e32 v124, v124, v130
	v_mul_f32_e32 v125, v125, v131
	v_mul_f32_e32 v120, v120, v130
	v_mul_f32_e32 v121, v121, v131
	v_cndmask_b32_e64 v130, 0, 1, s[12:13]
	v_cmp_ne_u32_e64 s[38:39], 1, v130
	s_andn2_b64 vcc, exec, s[12:13]
	v_mul_f32_e32 v118, v118, v146
	v_mul_f32_e32 v119, v119, v147
	s_cbranch_vccnz .LBB0_100
	v_mul_f32_e32 v131, 0xbfb8aa3b, v118
	v_exp_f32_e32 v131, v131
	v_mul_f32_e32 v130, 0xbfb8aa3b, v122
	v_exp_f32_e32 v130, v130
	v_mul_f32_e32 v147, 0xbfb8aa3b, v120
	v_add_f32_e32 v131, 1.0, v131
	v_rcp_f32_e32 v132, v131
	v_mul_f32_e32 v131, 0xbfb8aa3b, v123
	v_exp_f32_e32 v131, v131
	v_add_f32_e32 v130, 1.0, v130
	v_exp_f32_e32 v147, v147
	v_rcp_f32_e32 v130, v130
	v_add_f32_e32 v131, 1.0, v131
	v_rcp_f32_e32 v131, v131
	v_add_f32_e32 v147, 1.0, v147
	v_mul_f32_e32 v133, 0xbfb8aa3b, v119
	v_mul_f32_e32 v146, 0xbfb8aa3b, v124
	v_rcp_f32_e32 v148, v147
	v_mul_f32_e32 v147, 0xbfb8aa3b, v125
	v_mul_f32_e32 v122, v122, v130
	v_mul_f32_e32 v123, v123, v131
	v_mul_f32_e32 v130, 0xbfb8aa3b, v121
	v_exp_f32_e32 v133, v133
	v_exp_f32_e32 v146, v146
	v_exp_f32_e32 v147, v147
	v_exp_f32_e32 v130, v130
	v_add_f32_e32 v133, 1.0, v133
	v_add_f32_e32 v146, 1.0, v146
	v_add_f32_e32 v147, 1.0, v147
	v_add_f32_e32 v130, 1.0, v130
	v_rcp_f32_e32 v133, v133
	v_rcp_f32_e32 v146, v146
	v_rcp_f32_e32 v147, v147
	v_rcp_f32_e32 v149, v130
	v_mul_f32_e32 v118, v118, v132
	v_mul_f32_e32 v119, v119, v133
	v_mul_f32_e32 v124, v124, v146
	v_mul_f32_e32 v125, v125, v147
	v_mul_f32_e32 v120, v120, v148
	v_mul_f32_e32 v121, v121, v149
.LBB0_100:
	v_cvt_pk_bf16_f32 v122, v122, v123
	v_cvt_pk_bf16_f32 v123, v124, v125
	v_fmamk_f32 v124, v227, 0x3a800000, v231
	s_mov_b32 s10, 0x800000
	v_mul_f32_e32 v125, 0x4b800000, v124
	v_cmp_gt_f32_e32 vcc, s10, v124
	s_nop 1
	v_cndmask_b32_e32 v124, v124, v125, vcc
	v_rsq_f32_e32 v130, v124
	v_cvt_pk_bf16_f32 v124, v118, v119
	v_cvt_pk_bf16_f32 v125, v120, v121
	global_store_dwordx4 v[128:129], v[122:125], off offset:256
	v_mul_f32_e32 v118, 0x45800000, v130
	v_cndmask_b32_e32 v118, v130, v118, vcc
	v_mul_f32_e32 v116, v116, v118
	v_mul_f32_e32 v117, v117, v118
	v_mul_f32_e32 v114, v114, v118
	v_mul_f32_e32 v115, v115, v118
	v_mul_f32_e32 v112, v112, v118
	v_mul_f32_e32 v113, v113, v118
	s_and_b64 vcc, exec, s[38:39]
	v_mul_f32_e32 v110, v110, v118
	v_mul_f32_e32 v111, v111, v118
	s_cbranch_vccnz .LBB0_102
	v_mul_f32_e32 v119, 0xbfb8aa3b, v114
	v_exp_f32_e32 v119, v119
	s_nop 0
	v_add_f32_e32 v119, 1.0, v119
	v_rcp_f32_e32 v120, v119
	v_mul_f32_e32 v119, 0xbfb8aa3b, v110
	v_exp_f32_e32 v119, v119
	s_nop 0
	v_add_f32_e32 v119, 1.0, v119
	v_rcp_f32_e32 v122, v119
	v_mul_f32_e32 v119, 0xbfb8aa3b, v115
	v_exp_f32_e32 v119, v119
	s_nop 0
	v_add_f32_e32 v119, 1.0, v119
	v_rcp_f32_e32 v121, v119
	v_mul_f32_e32 v119, 0xbfb8aa3b, v111
	v_exp_f32_e32 v119, v119
	v_mul_f32_e32 v114, v114, v120
	v_mul_f32_e32 v115, v115, v121
	v_add_f32_e32 v119, 1.0, v119
	v_rcp_f32_e32 v123, v119
	v_mul_f32_e32 v119, 0xbfb8aa3b, v116
	v_exp_f32_e32 v119, v119
	v_mul_f32_e32 v110, v110, v122
	v_mul_f32_e32 v111, v111, v123
	v_add_f32_e32 v119, 1.0, v119
	v_rcp_f32_e32 v124, v119
	v_mul_f32_e32 v119, 0xbfb8aa3b, v112
	v_exp_f32_e32 v119, v119
	s_nop 0
	v_add_f32_e32 v119, 1.0, v119
	v_rcp_f32_e32 v128, v119
	v_mul_f32_e32 v119, 0xbfb8aa3b, v117
	v_exp_f32_e32 v119, v119
	s_nop 0
	v_add_f32_e32 v119, 1.0, v119
	v_rcp_f32_e32 v125, v119
	v_mul_f32_e32 v119, 0xbfb8aa3b, v113
	v_exp_f32_e32 v119, v119
	v_mul_f32_e32 v116, v116, v124
	v_mul_f32_e32 v117, v117, v125
	v_add_f32_e32 v119, 1.0, v119
	v_rcp_f32_e32 v129, v119
	s_nop 0
	v_mul_f32_e32 v112, v112, v128
	v_mul_f32_e32 v113, v113, v129
; __device__ __forceinline__ unsigned cvt_pk_bf16(float lo, float hi) { unsigned r; asm volatile("v_cvt_pk_bf16_f32 %0, %1, %2" : "=v"(r) : "v"(lo), "v"(hi)); return r; }
; __device__ __forceinline__ float silu_f(float x) { return x * __builtin_amdgcn_rcpf(1.0f + __expf(-x)); }
; __device__ __forceinline__ float silu_f(float x) { return x * __builtin_amdgcn_rcpf(1.0f + __expf(-x)); }
;     __device__ __forceinline__ void operator()(const f32x4 (&acc)[2][2][4][2], const Unit& u, int wr, int wc, int fr, int fq) const {
;     ...
;             for (int m = 0; m < 4; ++m) rs[ai][m] = rowss[row0 + ai * HALF + m * 16];
; #pragma unroll
;         for (int ai = 0; ai < 2; ++ai)
; #pragma unroll
;             for (int m = 0; m < 4; ++m) {
;                 const int row = row0 + ai * HALF + m * 16;
;                 const float r = rsqrtf(rs[ai][m] * (1.0f / 1024.0f) + RMS_EPS);
; #pragma unroll
;                 for (int bj = 0; bj < 2; ++bj) {
;                     f32x4 a = acc[ai][bj][m][0] * r, b = acc[ai][bj][m][1] * r;
;                     if (act) {
; #pragma unroll
;                         for (int e = 0; e < 4; ++e) { a[e] = silu_f(a[e]); b[e] = silu_f(b[e]); }
;                     }
;                     u32x4 w; w.x = cvt_pk_bf16(a[0], a[1]); w.y = cvt_pk_bf16(a[2], a[3]); w.z = cvt_pk_bf16(b[0], b[1]); w.w = cvt_pk_bf16(b[2], b[3]);
;                     *(u32x4*)(P + (size_t)row * ldp + col0 + bj * HALF) = w;
;                 }
.LBB0_102:
	v_or_b32_e32 v120, 16, v144
	v_cvt_pk_bf16_f32 v114, v114, v115
	v_cvt_pk_bf16_f32 v115, v116, v117
	v_cvt_pk_bf16_f32 v116, v110, v111
	v_mov_b64_e32 v[110:111], s[86:87]
	v_mov_b32_e32 v119, v118
	v_cvt_pk_bf16_f32 v117, v112, v113
	v_mad_i64_i32 v[110:111], s[10:11], v120, s55, v[110:111]
	v_mov_b32_e32 v112, v118
	v_mov_b32_e32 v113, v118
	v_lshl_add_u64 v[110:111], v[126:127], 1, v[110:111]
	v_mul_f32_e32 v108, v108, v112
	v_mul_f32_e32 v109, v109, v113
	v_mul_f32_e32 v106, v106, v118
	v_mul_f32_e32 v107, v107, v119
	v_mul_f32_e32 v104, v104, v112
	v_mul_f32_e32 v105, v105, v113
	s_and_b64 vcc, exec, s[38:39]
	v_mul_f32_e32 v102, v102, v118
	v_mul_f32_e32 v103, v103, v119
	global_store_dwordx4 v[110:111], v[114:117], off
	s_cbranch_vccnz .LBB0_104
	v_mul_f32_e32 v113, 0xbfb8aa3b, v102
	v_exp_f32_e32 v113, v113
	v_mul_f32_e32 v112, 0xbfb8aa3b, v106
	v_exp_f32_e32 v112, v112
	v_mul_f32_e32 v117, 0xbfb8aa3b, v104
	v_add_f32_e32 v113, 1.0, v113
	v_rcp_f32_e32 v114, v113
	v_mul_f32_e32 v113, 0xbfb8aa3b, v107
	v_exp_f32_e32 v113, v113
	v_add_f32_e32 v112, 1.0, v112
	v_exp_f32_e32 v117, v117
	v_rcp_f32_e32 v112, v112
	v_add_f32_e32 v113, 1.0, v113
	v_rcp_f32_e32 v113, v113
	v_add_f32_e32 v117, 1.0, v117
	v_mul_f32_e32 v115, 0xbfb8aa3b, v103
	v_mul_f32_e32 v116, 0xbfb8aa3b, v108
	v_rcp_f32_e32 v118, v117
	v_mul_f32_e32 v117, 0xbfb8aa3b, v109
	v_mul_f32_e32 v106, v106, v112
	v_mul_f32_e32 v107, v107, v113
	v_mul_f32_e32 v112, 0xbfb8aa3b, v105
	v_exp_f32_e32 v115, v115
	v_exp_f32_e32 v116, v116
	v_exp_f32_e32 v117, v117
	v_exp_f32_e32 v112, v112
	v_add_f32_e32 v115, 1.0, v115
	v_add_f32_e32 v116, 1.0, v116
	v_add_f32_e32 v117, 1.0, v117
	v_add_f32_e32 v112, 1.0, v112
	v_rcp_f32_e32 v115, v115
	v_rcp_f32_e32 v116, v116
	v_rcp_f32_e32 v117, v117
	v_rcp_f32_e32 v119, v112
	v_mul_f32_e32 v102, v102, v114
	v_mul_f32_e32 v103, v103, v115
	v_mul_f32_e32 v108, v108, v116
	v_mul_f32_e32 v109, v109, v117
	v_mul_f32_e32 v104, v104, v118
	v_mul_f32_e32 v105, v105, v119
.LBB0_104:
	v_cvt_pk_bf16_f32 v106, v106, v107
	v_cvt_pk_bf16_f32 v107, v108, v109
	v_fmamk_f32 v108, v228, 0x3a800000, v231
	s_mov_b32 s10, 0x800000
	v_mul_f32_e32 v109, 0x4b800000, v108
	v_cmp_gt_f32_e32 vcc, s10, v108
	s_nop 1
	v_cndmask_b32_e32 v108, v108, v109, vcc
	v_rsq_f32_e32 v112, v108
	v_cvt_pk_bf16_f32 v108, v102, v103
	v_cvt_pk_bf16_f32 v109, v104, v105
	global_store_dwordx4 v[110:111], v[106:109], off offset:256
	v_mul_f32_e32 v102, 0x45800000, v112
	v_cndmask_b32_e32 v102, v112, v102, vcc
	v_mul_f32_e32 v100, v100, v102
	v_mul_f32_e32 v101, v101, v102
	v_mul_f32_e32 v98, v98, v102
	v_mul_f32_e32 v99, v99, v102
	v_mul_f32_e32 v96, v96, v102
	v_mul_f32_e32 v97, v97, v102
	s_and_b64 vcc, exec, s[38:39]
	v_mul_f32_e32 v94, v94, v102
	v_mul_f32_e32 v95, v95, v102
	s_cbranch_vccnz .LBB0_106
	v_mul_f32_e32 v103, 0xbfb8aa3b, v98
	v_exp_f32_e32 v103, v103
	s_nop 0
	v_add_f32_e32 v103, 1.0, v103
	v_rcp_f32_e32 v104, v103
	v_mul_f32_e32 v103, 0xbfb8aa3b, v94
	v_exp_f32_e32 v103, v103
	s_nop 0
	v_add_f32_e32 v103, 1.0, v103
	v_rcp_f32_e32 v106, v103
	v_mul_f32_e32 v103, 0xbfb8aa3b, v99
	v_exp_f32_e32 v103, v103
	s_nop 0
	v_add_f32_e32 v103, 1.0, v103
	v_rcp_f32_e32 v105, v103
	v_mul_f32_e32 v103, 0xbfb8aa3b, v95
	v_exp_f32_e32 v103, v103
	v_mul_f32_e32 v98, v98, v104
	v_mul_f32_e32 v99, v99, v105
	v_add_f32_e32 v103, 1.0, v103
	v_rcp_f32_e32 v107, v103
	v_mul_f32_e32 v103, 0xbfb8aa3b, v100
	v_exp_f32_e32 v103, v103
	v_mul_f32_e32 v94, v94, v106
	v_mul_f32_e32 v95, v95, v107
	v_add_f32_e32 v103, 1.0, v103
	v_rcp_f32_e32 v108, v103
	v_mul_f32_e32 v103, 0xbfb8aa3b, v96
	v_exp_f32_e32 v103, v103
	s_nop 0
	v_add_f32_e32 v103, 1.0, v103
	v_rcp_f32_e32 v110, v103
	v_mul_f32_e32 v103, 0xbfb8aa3b, v101
	v_exp_f32_e32 v103, v103
	s_nop 0
	v_add_f32_e32 v103, 1.0, v103
	v_rcp_f32_e32 v109, v103
	v_mul_f32_e32 v103, 0xbfb8aa3b, v97
	v_exp_f32_e32 v103, v103
	v_mul_f32_e32 v100, v100, v108
	v_mul_f32_e32 v101, v101, v109
	v_add_f32_e32 v103, 1.0, v103
	v_rcp_f32_e32 v111, v103
	s_nop 0
	v_mul_f32_e32 v96, v96, v110
	v_mul_f32_e32 v97, v97, v111
.LBB0_106:
	v_or_b32_e32 v104, 32, v144
	v_cvt_pk_bf16_f32 v98, v98, v99
	v_cvt_pk_bf16_f32 v99, v100, v101
	v_cvt_pk_bf16_f32 v100, v94, v95
	v_mov_b64_e32 v[94:95], s[86:87]
	v_mov_b32_e32 v103, v102
	v_cvt_pk_bf16_f32 v101, v96, v97
	v_mad_i64_i32 v[94:95], s[10:11], v104, s55, v[94:95]
	v_mov_b32_e32 v96, v102
	v_mov_b32_e32 v97, v102
	v_lshl_add_u64 v[94:95], v[126:127], 1, v[94:95]
	v_mul_f32_e32 v92, v92, v96
	v_mul_f32_e32 v93, v93, v97
	v_mul_f32_e32 v90, v90, v102
	v_mul_f32_e32 v91, v91, v103
	v_mul_f32_e32 v88, v88, v96
	v_mul_f32_e32 v89, v89, v97
	s_and_b64 vcc, exec, s[38:39]
	v_mul_f32_e32 v86, v86, v102
	v_mul_f32_e32 v87, v87, v103
	global_store_dwordx4 v[94:95], v[98:101], off
	s_cbranch_vccnz .LBB0_108
	v_mul_f32_e32 v97, 0xbfb8aa3b, v86
	v_exp_f32_e32 v97, v97
	v_mul_f32_e32 v96, 0xbfb8aa3b, v90
	v_exp_f32_e32 v96, v96
	v_mul_f32_e32 v101, 0xbfb8aa3b, v88
	v_add_f32_e32 v97, 1.0, v97
	v_rcp_f32_e32 v98, v97
	v_mul_f32_e32 v97, 0xbfb8aa3b, v91
	v_exp_f32_e32 v97, v97
	v_add_f32_e32 v96, 1.0, v96
	v_exp_f32_e32 v101, v101
	v_rcp_f32_e32 v96, v96
	v_add_f32_e32 v97, 1.0, v97
	v_rcp_f32_e32 v97, v97
	v_add_f32_e32 v101, 1.0, v101
	v_mul_f32_e32 v99, 0xbfb8aa3b, v87
	v_mul_f32_e32 v100, 0xbfb8aa3b, v92
	v_rcp_f32_e32 v102, v101
	v_mul_f32_e32 v101, 0xbfb8aa3b, v93
	v_mul_f32_e32 v90, v90, v96
	v_mul_f32_e32 v91, v91, v97
	v_mul_f32_e32 v96, 0xbfb8aa3b, v89
	v_exp_f32_e32 v99, v99
	v_exp_f32_e32 v100, v100
	v_exp_f32_e32 v101, v101
	v_exp_f32_e32 v96, v96
	v_add_f32_e32 v99, 1.0, v99
	v_add_f32_e32 v100, 1.0, v100
	v_add_f32_e32 v101, 1.0, v101
	v_add_f32_e32 v96, 1.0, v96
	v_rcp_f32_e32 v99, v99
	v_rcp_f32_e32 v100, v100
	v_rcp_f32_e32 v101, v101
	v_rcp_f32_e32 v103, v96
	v_mul_f32_e32 v86, v86, v98
	v_mul_f32_e32 v87, v87, v99
	v_mul_f32_e32 v92, v92, v100
	v_mul_f32_e32 v93, v93, v101
	v_mul_f32_e32 v88, v88, v102
	v_mul_f32_e32 v89, v89, v103
; __device__ __forceinline__ unsigned cvt_pk_bf16(float lo, float hi) { unsigned r; asm volatile("v_cvt_pk_bf16_f32 %0, %1, %2" : "=v"(r) : "v"(lo), "v"(hi)); return r; }
; __device__ __forceinline__ float silu_f(float x) { return x * __builtin_amdgcn_rcpf(1.0f + __expf(-x)); }
; __device__ __forceinline__ float silu_f(float x) { return x * __builtin_amdgcn_rcpf(1.0f + __expf(-x)); }
;     __device__ __forceinline__ void operator()(const f32x4 (&acc)[2][2][4][2], const Unit& u, int wr, int wc, int fr, int fq) const {
;     ...
;             for (int m = 0; m < 4; ++m) rs[ai][m] = rowss[row0 + ai * HALF + m * 16];
; #pragma unroll
;         for (int ai = 0; ai < 2; ++ai)
; #pragma unroll
;             for (int m = 0; m < 4; ++m) {
;                 const int row = row0 + ai * HALF + m * 16;
;                 const float r = rsqrtf(rs[ai][m] * (1.0f / 1024.0f) + RMS_EPS);
; #pragma unroll
;                 for (int bj = 0; bj < 2; ++bj) {
;                     f32x4 a = acc[ai][bj][m][0] * r, b = acc[ai][bj][m][1] * r;
;                     if (act) {
; #pragma unroll
;                         for (int e = 0; e < 4; ++e) { a[e] = silu_f(a[e]); b[e] = silu_f(b[e]); }
;                     }
;                     u32x4 w; w.x = cvt_pk_bf16(a[0], a[1]); w.y = cvt_pk_bf16(a[2], a[3]); w.z = cvt_pk_bf16(b[0], b[1]); w.w = cvt_pk_bf16(b[2], b[3]);
;                     *(u32x4*)(P + (size_t)row * ldp + col0 + bj * HALF) = w;
;                 }
.LBB0_108:
	v_cvt_pk_bf16_f32 v90, v90, v91
	v_cvt_pk_bf16_f32 v91, v92, v93
	v_fmamk_f32 v92, v229, 0x3a800000, v231
	s_mov_b32 s10, 0x800000
	v_mul_f32_e32 v93, 0x4b800000, v92
	v_cmp_gt_f32_e32 vcc, s10, v92
	s_nop 1
	v_cndmask_b32_e32 v92, v92, v93, vcc
	v_rsq_f32_e32 v96, v92
	v_cvt_pk_bf16_f32 v92, v86, v87
	v_cvt_pk_bf16_f32 v93, v88, v89
	global_store_dwordx4 v[94:95], v[90:93], off offset:256
	v_mul_f32_e32 v86, 0x45800000, v96
	v_cndmask_b32_e32 v86, v96, v86, vcc
	v_mul_f32_e32 v84, v84, v86
	v_mul_f32_e32 v85, v85, v86
	v_mul_f32_e32 v82, v82, v86
	v_mul_f32_e32 v83, v83, v86
	v_mul_f32_e32 v80, v80, v86
	v_mul_f32_e32 v81, v81, v86
	s_and_b64 vcc, exec, s[38:39]
	v_mul_f32_e32 v78, v78, v86
	v_mul_f32_e32 v79, v79, v86
	s_cbranch_vccnz .LBB0_110
	v_mul_f32_e32 v87, 0xbfb8aa3b, v82
	v_exp_f32_e32 v87, v87
	s_nop 0
	v_add_f32_e32 v87, 1.0, v87
	v_rcp_f32_e32 v88, v87
	v_mul_f32_e32 v87, 0xbfb8aa3b, v78
	v_exp_f32_e32 v87, v87
	s_nop 0
	v_add_f32_e32 v87, 1.0, v87
	v_rcp_f32_e32 v90, v87
	v_mul_f32_e32 v87, 0xbfb8aa3b, v83
	v_exp_f32_e32 v87, v87
	s_nop 0
	v_add_f32_e32 v87, 1.0, v87
	v_rcp_f32_e32 v89, v87
	v_mul_f32_e32 v87, 0xbfb8aa3b, v79
	v_exp_f32_e32 v87, v87
	v_mul_f32_e32 v82, v82, v88
	v_mul_f32_e32 v83, v83, v89
	v_add_f32_e32 v87, 1.0, v87
	v_rcp_f32_e32 v91, v87
	v_mul_f32_e32 v87, 0xbfb8aa3b, v84
	v_exp_f32_e32 v87, v87
	v_mul_f32_e32 v78, v78, v90
	v_mul_f32_e32 v79, v79, v91
	v_add_f32_e32 v87, 1.0, v87
	v_rcp_f32_e32 v92, v87
	v_mul_f32_e32 v87, 0xbfb8aa3b, v80
	v_exp_f32_e32 v87, v87
	s_nop 0
	v_add_f32_e32 v87, 1.0, v87
	v_rcp_f32_e32 v94, v87
	v_mul_f32_e32 v87, 0xbfb8aa3b, v85
	v_exp_f32_e32 v87, v87
	s_nop 0
	v_add_f32_e32 v87, 1.0, v87
	v_rcp_f32_e32 v93, v87
	v_mul_f32_e32 v87, 0xbfb8aa3b, v81
	v_exp_f32_e32 v87, v87
	v_mul_f32_e32 v84, v84, v92
	v_mul_f32_e32 v85, v85, v93
	v_add_f32_e32 v87, 1.0, v87
	v_rcp_f32_e32 v95, v87
	s_nop 0
	v_mul_f32_e32 v80, v80, v94
	v_mul_f32_e32 v81, v81, v95
.LBB0_110:
	v_or_b32_e32 v88, 48, v144
	v_cvt_pk_bf16_f32 v82, v82, v83
	v_cvt_pk_bf16_f32 v83, v84, v85
	v_cvt_pk_bf16_f32 v84, v78, v79
	v_mov_b64_e32 v[78:79], s[86:87]
	v_mov_b32_e32 v87, v86
	v_cvt_pk_bf16_f32 v85, v80, v81
	v_mad_i64_i32 v[78:79], s[10:11], v88, s55, v[78:79]
	v_mov_b32_e32 v80, v86
	v_mov_b32_e32 v81, v86
	v_lshl_add_u64 v[78:79], v[126:127], 1, v[78:79]
	v_mul_f32_e32 v76, v76, v80
	v_mul_f32_e32 v77, v77, v81
	v_mul_f32_e32 v74, v74, v86
	v_mul_f32_e32 v75, v75, v87
	v_mul_f32_e32 v72, v72, v80
	v_mul_f32_e32 v73, v73, v81
	s_and_b64 vcc, exec, s[38:39]
	v_mul_f32_e32 v70, v70, v86
	v_mul_f32_e32 v71, v71, v87
	global_store_dwordx4 v[78:79], v[82:85], off
	s_cbranch_vccnz .LBB0_112
	v_mul_f32_e32 v81, 0xbfb8aa3b, v70
	v_exp_f32_e32 v81, v81
	v_mul_f32_e32 v80, 0xbfb8aa3b, v74
	v_exp_f32_e32 v80, v80
	v_mul_f32_e32 v85, 0xbfb8aa3b, v72
	v_add_f32_e32 v81, 1.0, v81
	v_rcp_f32_e32 v82, v81
	v_mul_f32_e32 v81, 0xbfb8aa3b, v75
	v_exp_f32_e32 v81, v81
	v_add_f32_e32 v80, 1.0, v80
	v_exp_f32_e32 v85, v85
	v_rcp_f32_e32 v80, v80
	v_add_f32_e32 v81, 1.0, v81
	v_rcp_f32_e32 v81, v81
	v_add_f32_e32 v85, 1.0, v85
	v_mul_f32_e32 v83, 0xbfb8aa3b, v71
	v_mul_f32_e32 v84, 0xbfb8aa3b, v76
	v_rcp_f32_e32 v86, v85
	v_mul_f32_e32 v85, 0xbfb8aa3b, v77
	v_mul_f32_e32 v74, v74, v80
	v_mul_f32_e32 v75, v75, v81
	v_mul_f32_e32 v80, 0xbfb8aa3b, v73
	v_exp_f32_e32 v83, v83
	v_exp_f32_e32 v84, v84
	v_exp_f32_e32 v85, v85
	v_exp_f32_e32 v80, v80
	v_add_f32_e32 v83, 1.0, v83
	v_add_f32_e32 v84, 1.0, v84
	v_add_f32_e32 v85, 1.0, v85
	v_add_f32_e32 v80, 1.0, v80
	v_rcp_f32_e32 v83, v83
	v_rcp_f32_e32 v84, v84
	v_rcp_f32_e32 v85, v85
	v_rcp_f32_e32 v87, v80
	v_mul_f32_e32 v70, v70, v82
	v_mul_f32_e32 v71, v71, v83
	v_mul_f32_e32 v76, v76, v84
	v_mul_f32_e32 v77, v77, v85
	v_mul_f32_e32 v72, v72, v86
	v_mul_f32_e32 v73, v73, v87
.LBB0_112:
	v_cvt_pk_bf16_f32 v74, v74, v75
	v_cvt_pk_bf16_f32 v75, v76, v77
	v_fmamk_f32 v76, v238, 0x3a800000, v231
	s_mov_b32 s10, 0x800000
	v_mul_f32_e32 v77, 0x4b800000, v76
	v_cmp_gt_f32_e32 vcc, s10, v76
	s_nop 1
	v_cndmask_b32_e32 v76, v76, v77, vcc
	v_rsq_f32_e32 v80, v76
	v_cvt_pk_bf16_f32 v76, v70, v71
	v_cvt_pk_bf16_f32 v77, v72, v73
	global_store_dwordx4 v[78:79], v[74:77], off offset:256
	v_mul_f32_e32 v70, 0x45800000, v80
	v_cndmask_b32_e32 v70, v80, v70, vcc
	v_mul_f32_e32 v68, v68, v70
	v_mul_f32_e32 v69, v69, v70
	v_mul_f32_e32 v66, v66, v70
	v_mul_f32_e32 v67, v67, v70
	v_mul_f32_e32 v64, v64, v70
	v_mul_f32_e32 v65, v65, v70
	s_and_b64 vcc, exec, s[38:39]
	v_mul_f32_e32 v62, v62, v70
	v_mul_f32_e32 v63, v63, v70
	s_cbranch_vccnz .LBB0_114
	v_mul_f32_e32 v71, 0xbfb8aa3b, v66
	v_exp_f32_e32 v71, v71
	s_nop 0
	v_add_f32_e32 v71, 1.0, v71
	v_rcp_f32_e32 v72, v71
	v_mul_f32_e32 v71, 0xbfb8aa3b, v62
	v_exp_f32_e32 v71, v71
	s_nop 0
	v_add_f32_e32 v71, 1.0, v71
	v_rcp_f32_e32 v74, v71
	v_mul_f32_e32 v71, 0xbfb8aa3b, v67
	v_exp_f32_e32 v71, v71
	s_nop 0
	v_add_f32_e32 v71, 1.0, v71
	v_rcp_f32_e32 v73, v71
	v_mul_f32_e32 v71, 0xbfb8aa3b, v63
	v_exp_f32_e32 v71, v71
	v_mul_f32_e32 v66, v66, v72
	v_mul_f32_e32 v67, v67, v73
	v_add_f32_e32 v71, 1.0, v71
	v_rcp_f32_e32 v75, v71
	v_mul_f32_e32 v71, 0xbfb8aa3b, v68
	v_exp_f32_e32 v71, v71
	v_mul_f32_e32 v62, v62, v74
	v_mul_f32_e32 v63, v63, v75
	v_add_f32_e32 v71, 1.0, v71
	v_rcp_f32_e32 v76, v71
	v_mul_f32_e32 v71, 0xbfb8aa3b, v64
	v_exp_f32_e32 v71, v71
	s_nop 0
	v_add_f32_e32 v71, 1.0, v71
	v_rcp_f32_e32 v78, v71
	v_mul_f32_e32 v71, 0xbfb8aa3b, v69
	v_exp_f32_e32 v71, v71
	s_nop 0
	v_add_f32_e32 v71, 1.0, v71
	v_rcp_f32_e32 v77, v71
	v_mul_f32_e32 v71, 0xbfb8aa3b, v65
	v_exp_f32_e32 v71, v71
	v_mul_f32_e32 v68, v68, v76
	v_mul_f32_e32 v69, v69, v77
	v_add_f32_e32 v71, 1.0, v71
	v_rcp_f32_e32 v79, v71
	s_nop 0
	v_mul_f32_e32 v64, v64, v78
	v_mul_f32_e32 v65, v65, v79
; __device__ __forceinline__ unsigned cvt_pk_bf16(float lo, float hi) { unsigned r; asm volatile("v_cvt_pk_bf16_f32 %0, %1, %2" : "=v"(r) : "v"(lo), "v"(hi)); return r; }
; __device__ __forceinline__ float silu_f(float x) { return x * __builtin_amdgcn_rcpf(1.0f + __expf(-x)); }
; __device__ __forceinline__ float silu_f(float x) { return x * __builtin_amdgcn_rcpf(1.0f + __expf(-x)); }
;     __device__ __forceinline__ void operator()(const f32x4 (&acc)[2][2][4][2], const Unit& u, int wr, int wc, int fr, int fq) const {
;     ...
;             for (int m = 0; m < 4; ++m) rs[ai][m] = rowss[row0 + ai * HALF + m * 16];
; #pragma unroll
;         for (int ai = 0; ai < 2; ++ai)
; #pragma unroll
;             for (int m = 0; m < 4; ++m) {
;                 const int row = row0 + ai * HALF + m * 16;
;                 const float r = rsqrtf(rs[ai][m] * (1.0f / 1024.0f) + RMS_EPS);
; #pragma unroll
;                 for (int bj = 0; bj < 2; ++bj) {
;                     f32x4 a = acc[ai][bj][m][0] * r, b = acc[ai][bj][m][1] * r;
;                     if (act) {
; #pragma unroll
;                         for (int e = 0; e < 4; ++e) { a[e] = silu_f(a[e]); b[e] = silu_f(b[e]); }
;                     }
;                     u32x4 w; w.x = cvt_pk_bf16(a[0], a[1]); w.y = cvt_pk_bf16(a[2], a[3]); w.z = cvt_pk_bf16(b[0], b[1]); w.w = cvt_pk_bf16(b[2], b[3]);
;                     *(u32x4*)(P + (size_t)row * ldp + col0 + bj * HALF) = w;
;                 }
.LBB0_114:
	v_add_u32_e32 v72, 0x80, v144
	v_cvt_pk_bf16_f32 v66, v66, v67
	v_cvt_pk_bf16_f32 v67, v68, v69
	v_cvt_pk_bf16_f32 v68, v62, v63
	v_mov_b64_e32 v[62:63], s[86:87]
	v_mov_b32_e32 v71, v70
	v_cvt_pk_bf16_f32 v69, v64, v65
	v_mad_i64_i32 v[62:63], s[10:11], v72, s55, v[62:63]
	v_mov_b32_e32 v64, v70
	v_mov_b32_e32 v65, v70
	v_lshl_add_u64 v[62:63], v[126:127], 1, v[62:63]
	v_mul_f32_e32 v60, v60, v64
	v_mul_f32_e32 v61, v61, v65
	v_mul_f32_e32 v58, v58, v70
	v_mul_f32_e32 v59, v59, v71
	v_mul_f32_e32 v56, v56, v64
	v_mul_f32_e32 v57, v57, v65
	s_and_b64 vcc, exec, s[38:39]
	v_mul_f32_e32 v54, v54, v70
	v_mul_f32_e32 v55, v55, v71
	global_store_dwordx4 v[62:63], v[66:69], off
	s_cbranch_vccnz .LBB0_116
	v_mul_f32_e32 v65, 0xbfb8aa3b, v54
	v_exp_f32_e32 v65, v65
	v_mul_f32_e32 v64, 0xbfb8aa3b, v58
	v_exp_f32_e32 v64, v64
	v_mul_f32_e32 v69, 0xbfb8aa3b, v56
	v_add_f32_e32 v65, 1.0, v65
	v_rcp_f32_e32 v66, v65
	v_mul_f32_e32 v65, 0xbfb8aa3b, v59
	v_exp_f32_e32 v65, v65
	v_add_f32_e32 v64, 1.0, v64
	v_exp_f32_e32 v69, v69
	v_rcp_f32_e32 v64, v64
	v_add_f32_e32 v65, 1.0, v65
	v_rcp_f32_e32 v65, v65
	v_add_f32_e32 v69, 1.0, v69
	v_mul_f32_e32 v67, 0xbfb8aa3b, v55
	v_mul_f32_e32 v68, 0xbfb8aa3b, v60
	v_rcp_f32_e32 v70, v69
	v_mul_f32_e32 v69, 0xbfb8aa3b, v61
	v_mul_f32_e32 v58, v58, v64
	v_mul_f32_e32 v59, v59, v65
	v_mul_f32_e32 v64, 0xbfb8aa3b, v57
	v_exp_f32_e32 v67, v67
	v_exp_f32_e32 v68, v68
	v_exp_f32_e32 v69, v69
	v_exp_f32_e32 v64, v64
	v_add_f32_e32 v67, 1.0, v67
	v_add_f32_e32 v68, 1.0, v68
	v_add_f32_e32 v69, 1.0, v69
	v_add_f32_e32 v64, 1.0, v64
	v_rcp_f32_e32 v67, v67
	v_rcp_f32_e32 v68, v68
	v_rcp_f32_e32 v69, v69
	v_rcp_f32_e32 v71, v64
	v_mul_f32_e32 v54, v54, v66
	v_mul_f32_e32 v55, v55, v67
	v_mul_f32_e32 v60, v60, v68
	v_mul_f32_e32 v61, v61, v69
	v_mul_f32_e32 v56, v56, v70
	v_mul_f32_e32 v57, v57, v71
.LBB0_116:
	v_cvt_pk_bf16_f32 v58, v58, v59
	v_cvt_pk_bf16_f32 v59, v60, v61
	v_fmamk_f32 v60, v239, 0x3a800000, v231
	s_mov_b32 s10, 0x800000
	v_mul_f32_e32 v61, 0x4b800000, v60
	v_cmp_gt_f32_e32 vcc, s10, v60
	s_nop 1
	v_cndmask_b32_e32 v60, v60, v61, vcc
	v_rsq_f32_e32 v64, v60
	v_cvt_pk_bf16_f32 v60, v54, v55
	v_cvt_pk_bf16_f32 v61, v56, v57
	global_store_dwordx4 v[62:63], v[58:61], off offset:256
	v_mul_f32_e32 v54, 0x45800000, v64
	v_cndmask_b32_e32 v54, v64, v54, vcc
	v_mul_f32_e32 v52, v52, v54
	v_mul_f32_e32 v53, v53, v54
	v_mul_f32_e32 v50, v50, v54
	v_mul_f32_e32 v51, v51, v54
	v_mul_f32_e32 v48, v48, v54
	v_mul_f32_e32 v49, v49, v54
	s_and_b64 vcc, exec, s[38:39]
	v_mul_f32_e32 v46, v46, v54
	v_mul_f32_e32 v47, v47, v54
	s_cbranch_vccnz .LBB0_118
	v_mul_f32_e32 v55, 0xbfb8aa3b, v50
	v_exp_f32_e32 v55, v55
	s_nop 0
	v_add_f32_e32 v55, 1.0, v55
	v_rcp_f32_e32 v56, v55
	v_mul_f32_e32 v55, 0xbfb8aa3b, v46
	v_exp_f32_e32 v55, v55
	s_nop 0
	v_add_f32_e32 v55, 1.0, v55
	v_rcp_f32_e32 v58, v55
	v_mul_f32_e32 v55, 0xbfb8aa3b, v51
	v_exp_f32_e32 v55, v55
	s_nop 0
	v_add_f32_e32 v55, 1.0, v55
	v_rcp_f32_e32 v57, v55
	v_mul_f32_e32 v55, 0xbfb8aa3b, v47
	v_exp_f32_e32 v55, v55
	v_mul_f32_e32 v50, v50, v56
	v_mul_f32_e32 v51, v51, v57
	v_add_f32_e32 v55, 1.0, v55
	v_rcp_f32_e32 v59, v55
	v_mul_f32_e32 v55, 0xbfb8aa3b, v52
	v_exp_f32_e32 v55, v55
	v_mul_f32_e32 v46, v46, v58
	v_mul_f32_e32 v47, v47, v59
	v_add_f32_e32 v55, 1.0, v55
	v_rcp_f32_e32 v60, v55
	v_mul_f32_e32 v55, 0xbfb8aa3b, v48
	v_exp_f32_e32 v55, v55
	s_nop 0
	v_add_f32_e32 v55, 1.0, v55
	v_rcp_f32_e32 v62, v55
	v_mul_f32_e32 v55, 0xbfb8aa3b, v53
	v_exp_f32_e32 v55, v55
	s_nop 0
	v_add_f32_e32 v55, 1.0, v55
	v_rcp_f32_e32 v61, v55
	v_mul_f32_e32 v55, 0xbfb8aa3b, v49
	v_exp_f32_e32 v55, v55
	v_mul_f32_e32 v52, v52, v60
	v_mul_f32_e32 v53, v53, v61
	v_add_f32_e32 v55, 1.0, v55
	v_rcp_f32_e32 v63, v55
	s_nop 0
	v_mul_f32_e32 v48, v48, v62
	v_mul_f32_e32 v49, v49, v63
.LBB0_118:
	v_add_u32_e32 v56, 0x90, v144
	v_cvt_pk_bf16_f32 v50, v50, v51
	v_cvt_pk_bf16_f32 v51, v52, v53
	v_cvt_pk_bf16_f32 v52, v46, v47
	v_mov_b64_e32 v[46:47], s[86:87]
	v_mov_b32_e32 v55, v54
	v_cvt_pk_bf16_f32 v53, v48, v49
	v_mad_i64_i32 v[46:47], s[10:11], v56, s55, v[46:47]
	v_mov_b32_e32 v48, v54
	v_mov_b32_e32 v49, v54
	v_lshl_add_u64 v[46:47], v[126:127], 1, v[46:47]
	v_mul_f32_e32 v44, v44, v48
	v_mul_f32_e32 v45, v45, v49
	v_mul_f32_e32 v42, v42, v54
	v_mul_f32_e32 v43, v43, v55
	v_mul_f32_e32 v40, v40, v48
	v_mul_f32_e32 v41, v41, v49
	s_and_b64 vcc, exec, s[38:39]
	v_mul_f32_e32 v38, v38, v54
	v_mul_f32_e32 v39, v39, v55
	global_store_dwordx4 v[46:47], v[50:53], off
	s_cbranch_vccnz .LBB0_120
	v_mul_f32_e32 v49, 0xbfb8aa3b, v38
	v_exp_f32_e32 v49, v49
	v_mul_f32_e32 v48, 0xbfb8aa3b, v42
	v_exp_f32_e32 v48, v48
	v_mul_f32_e32 v53, 0xbfb8aa3b, v40
	v_add_f32_e32 v49, 1.0, v49
	v_rcp_f32_e32 v50, v49
	v_mul_f32_e32 v49, 0xbfb8aa3b, v43
	v_exp_f32_e32 v49, v49
	v_add_f32_e32 v48, 1.0, v48
	v_exp_f32_e32 v53, v53
	v_rcp_f32_e32 v48, v48
	v_add_f32_e32 v49, 1.0, v49
	v_rcp_f32_e32 v49, v49
	v_add_f32_e32 v53, 1.0, v53
	v_mul_f32_e32 v51, 0xbfb8aa3b, v39
	v_mul_f32_e32 v52, 0xbfb8aa3b, v44
	v_rcp_f32_e32 v54, v53
	v_mul_f32_e32 v53, 0xbfb8aa3b, v45
	v_mul_f32_e32 v42, v42, v48
	v_mul_f32_e32 v43, v43, v49
	v_mul_f32_e32 v48, 0xbfb8aa3b, v41
	v_exp_f32_e32 v51, v51
	v_exp_f32_e32 v52, v52
	v_exp_f32_e32 v53, v53
	v_exp_f32_e32 v48, v48
	v_add_f32_e32 v51, 1.0, v51
	v_add_f32_e32 v52, 1.0, v52
	v_add_f32_e32 v53, 1.0, v53
	v_add_f32_e32 v48, 1.0, v48
	v_rcp_f32_e32 v51, v51
	v_rcp_f32_e32 v52, v52
	v_rcp_f32_e32 v53, v53
	v_rcp_f32_e32 v55, v48
	v_mul_f32_e32 v38, v38, v50
	v_mul_f32_e32 v39, v39, v51
	v_mul_f32_e32 v44, v44, v52
	v_mul_f32_e32 v45, v45, v53
	v_mul_f32_e32 v40, v40, v54
	v_mul_f32_e32 v41, v41, v55
; __device__ __forceinline__ unsigned cvt_pk_bf16(float lo, float hi) { unsigned r; asm volatile("v_cvt_pk_bf16_f32 %0, %1, %2" : "=v"(r) : "v"(lo), "v"(hi)); return r; }
; __device__ __forceinline__ float silu_f(float x) { return x * __builtin_amdgcn_rcpf(1.0f + __expf(-x)); }
; __device__ __forceinline__ float silu_f(float x) { return x * __builtin_amdgcn_rcpf(1.0f + __expf(-x)); }
;     __device__ __forceinline__ void operator()(const f32x4 (&acc)[2][2][4][2], const Unit& u, int wr, int wc, int fr, int fq) const {
;     ...
;             for (int m = 0; m < 4; ++m) rs[ai][m] = rowss[row0 + ai * HALF + m * 16];
; #pragma unroll
;         for (int ai = 0; ai < 2; ++ai)
; #pragma unroll
;             for (int m = 0; m < 4; ++m) {
;                 const int row = row0 + ai * HALF + m * 16;
;                 const float r = rsqrtf(rs[ai][m] * (1.0f / 1024.0f) + RMS_EPS);
; #pragma unroll
;                 for (int bj = 0; bj < 2; ++bj) {
;                     f32x4 a = acc[ai][bj][m][0] * r, b = acc[ai][bj][m][1] * r;
;                     if (act) {
; #pragma unroll
;                         for (int e = 0; e < 4; ++e) { a[e] = silu_f(a[e]); b[e] = silu_f(b[e]); }
;                     }
;                     u32x4 w; w.x = cvt_pk_bf16(a[0], a[1]); w.y = cvt_pk_bf16(a[2], a[3]); w.z = cvt_pk_bf16(b[0], b[1]); w.w = cvt_pk_bf16(b[2], b[3]);
;                     *(u32x4*)(P + (size_t)row * ldp + col0 + bj * HALF) = w;
;                 }
.LBB0_120:
	v_cvt_pk_bf16_f32 v42, v42, v43
	v_cvt_pk_bf16_f32 v43, v44, v45
	v_fmamk_f32 v44, v240, 0x3a800000, v231
	s_mov_b32 s10, 0x800000
	v_mul_f32_e32 v45, 0x4b800000, v44
	v_cmp_gt_f32_e32 vcc, s10, v44
	s_nop 1
	v_cndmask_b32_e32 v44, v44, v45, vcc
	v_rsq_f32_e32 v48, v44
	v_cvt_pk_bf16_f32 v44, v38, v39
	v_cvt_pk_bf16_f32 v45, v40, v41
	global_store_dwordx4 v[46:47], v[42:45], off offset:256
	v_mul_f32_e32 v38, 0x45800000, v48
	v_cndmask_b32_e32 v38, v48, v38, vcc
	v_mul_f32_e32 v36, v36, v38
	v_mul_f32_e32 v37, v37, v38
	v_mul_f32_e32 v34, v34, v38
	v_mul_f32_e32 v35, v35, v38
	v_mul_f32_e32 v32, v32, v38
	v_mul_f32_e32 v33, v33, v38
	s_and_b64 vcc, exec, s[38:39]
	v_mul_f32_e32 v30, v30, v38
	v_mul_f32_e32 v31, v31, v38
	s_cbranch_vccnz .LBB0_122
	v_mul_f32_e32 v39, 0xbfb8aa3b, v34
	v_exp_f32_e32 v39, v39
	s_nop 0
	v_add_f32_e32 v39, 1.0, v39
	v_rcp_f32_e32 v40, v39
	v_mul_f32_e32 v39, 0xbfb8aa3b, v30
	v_exp_f32_e32 v39, v39
	s_nop 0
	v_add_f32_e32 v39, 1.0, v39
	v_rcp_f32_e32 v42, v39
	v_mul_f32_e32 v39, 0xbfb8aa3b, v35
	v_exp_f32_e32 v39, v39
	s_nop 0
	v_add_f32_e32 v39, 1.0, v39
	v_rcp_f32_e32 v41, v39
	v_mul_f32_e32 v39, 0xbfb8aa3b, v31
	v_exp_f32_e32 v39, v39
	v_mul_f32_e32 v34, v34, v40
	v_mul_f32_e32 v35, v35, v41
	v_add_f32_e32 v39, 1.0, v39
	v_rcp_f32_e32 v43, v39
	v_mul_f32_e32 v39, 0xbfb8aa3b, v36
	v_exp_f32_e32 v39, v39
	v_mul_f32_e32 v30, v30, v42
	v_mul_f32_e32 v31, v31, v43
	v_add_f32_e32 v39, 1.0, v39
	v_rcp_f32_e32 v44, v39
	v_mul_f32_e32 v39, 0xbfb8aa3b, v32
	v_exp_f32_e32 v39, v39
	s_nop 0
	v_add_f32_e32 v39, 1.0, v39
	v_rcp_f32_e32 v46, v39
	v_mul_f32_e32 v39, 0xbfb8aa3b, v37
	v_exp_f32_e32 v39, v39
	s_nop 0
	v_add_f32_e32 v39, 1.0, v39
	v_rcp_f32_e32 v45, v39
	v_mul_f32_e32 v39, 0xbfb8aa3b, v33
	v_exp_f32_e32 v39, v39
	v_mul_f32_e32 v36, v36, v44
	v_mul_f32_e32 v37, v37, v45
	v_add_f32_e32 v39, 1.0, v39
	v_rcp_f32_e32 v47, v39
	s_nop 0
	v_mul_f32_e32 v32, v32, v46
	v_mul_f32_e32 v33, v33, v47
.LBB0_122:
	v_add_u32_e32 v40, 0xa0, v144
	v_cvt_pk_bf16_f32 v34, v34, v35
	v_cvt_pk_bf16_f32 v35, v36, v37
	v_cvt_pk_bf16_f32 v36, v30, v31
	v_mov_b64_e32 v[30:31], s[86:87]
	v_mov_b32_e32 v39, v38
	v_cvt_pk_bf16_f32 v37, v32, v33
	v_mad_i64_i32 v[30:31], s[10:11], v40, s55, v[30:31]
	v_mov_b32_e32 v32, v38
	v_mov_b32_e32 v33, v38
	v_lshl_add_u64 v[30:31], v[126:127], 1, v[30:31]
	v_mul_f32_e32 v28, v28, v32
	v_mul_f32_e32 v29, v29, v33
	v_mul_f32_e32 v26, v26, v38
	v_mul_f32_e32 v27, v27, v39
	v_mul_f32_e32 v24, v24, v32
	v_mul_f32_e32 v25, v25, v33
	s_and_b64 vcc, exec, s[38:39]
	v_mul_f32_e32 v22, v22, v38
	v_mul_f32_e32 v23, v23, v39
	global_store_dwordx4 v[30:31], v[34:37], off
	s_cbranch_vccnz .LBB0_124
	v_mul_f32_e32 v33, 0xbfb8aa3b, v22
	v_exp_f32_e32 v33, v33
	v_mul_f32_e32 v32, 0xbfb8aa3b, v26
	v_exp_f32_e32 v32, v32
	v_mul_f32_e32 v37, 0xbfb8aa3b, v24
	v_add_f32_e32 v33, 1.0, v33
	v_rcp_f32_e32 v34, v33
	v_mul_f32_e32 v33, 0xbfb8aa3b, v27
	v_exp_f32_e32 v33, v33
	v_add_f32_e32 v32, 1.0, v32
	v_exp_f32_e32 v37, v37
	v_rcp_f32_e32 v32, v32
	v_add_f32_e32 v33, 1.0, v33
	v_rcp_f32_e32 v33, v33
	v_add_f32_e32 v37, 1.0, v37
	v_mul_f32_e32 v35, 0xbfb8aa3b, v23
	v_mul_f32_e32 v36, 0xbfb8aa3b, v28
	v_rcp_f32_e32 v38, v37
	v_mul_f32_e32 v37, 0xbfb8aa3b, v29
	v_mul_f32_e32 v26, v26, v32
	v_mul_f32_e32 v27, v27, v33
	v_mul_f32_e32 v32, 0xbfb8aa3b, v25
	v_exp_f32_e32 v35, v35
	v_exp_f32_e32 v36, v36
	v_exp_f32_e32 v37, v37
	v_exp_f32_e32 v32, v32
	v_add_f32_e32 v35, 1.0, v35
	v_add_f32_e32 v36, 1.0, v36
	v_add_f32_e32 v37, 1.0, v37
	v_add_f32_e32 v32, 1.0, v32
	v_rcp_f32_e32 v35, v35
	v_rcp_f32_e32 v36, v36
	v_rcp_f32_e32 v37, v37
	v_rcp_f32_e32 v39, v32
	v_mul_f32_e32 v22, v22, v34
	v_mul_f32_e32 v23, v23, v35
	v_mul_f32_e32 v28, v28, v36
	v_mul_f32_e32 v29, v29, v37
	v_mul_f32_e32 v24, v24, v38
	v_mul_f32_e32 v25, v25, v39
; __device__ __forceinline__ unsigned cvt_pk_bf16(float lo, float hi) { unsigned r; asm volatile("v_cvt_pk_bf16_f32 %0, %1, %2" : "=v"(r) : "v"(lo), "v"(hi)); return r; }
; __device__ __forceinline__ float silu_f(float x) { return x * __builtin_amdgcn_rcpf(1.0f + __expf(-x)); }
; __device__ __forceinline__ float silu_f(float x) { return x * __builtin_amdgcn_rcpf(1.0f + __expf(-x)); }
;     __device__ __forceinline__ void operator()(const f32x4 (&acc)[2][2][4][2], const Unit& u, int wr, int wc, int fr, int fq) const {
;     ...
;             for (int m = 0; m < 4; ++m) rs[ai][m] = rowss[row0 + ai * HALF + m * 16];
; #pragma unroll
;         for (int ai = 0; ai < 2; ++ai)
; #pragma unroll
;             for (int m = 0; m < 4; ++m) {
;                 const int row = row0 + ai * HALF + m * 16;
;                 const float r = rsqrtf(rs[ai][m] * (1.0f / 1024.0f) + RMS_EPS);
; #pragma unroll
;                 for (int bj = 0; bj < 2; ++bj) {
;                     f32x4 a = acc[ai][bj][m][0] * r, b = acc[ai][bj][m][1] * r;
;                     if (act) {
; #pragma unroll
;                         for (int e = 0; e < 4; ++e) { a[e] = silu_f(a[e]); b[e] = silu_f(b[e]); }
;                     }
;                     u32x4 w; w.x = cvt_pk_bf16(a[0], a[1]); w.y = cvt_pk_bf16(a[2], a[3]); w.z = cvt_pk_bf16(b[0], b[1]); w.w = cvt_pk_bf16(b[2], b[3]);
;                     *(u32x4*)(P + (size_t)row * ldp + col0 + bj * HALF) = w;
;                 }
.LBB0_124:
	v_cvt_pk_bf16_f32 v26, v26, v27
	v_cvt_pk_bf16_f32 v27, v28, v29
	v_fmamk_f32 v28, v241, 0x3a800000, v231
	s_mov_b32 s10, 0x800000
	v_mul_f32_e32 v29, 0x4b800000, v28
	v_cmp_gt_f32_e32 vcc, s10, v28
	s_nop 1
	v_cndmask_b32_e32 v28, v28, v29, vcc
	v_rsq_f32_e32 v32, v28
	v_cvt_pk_bf16_f32 v28, v22, v23
	v_cvt_pk_bf16_f32 v29, v24, v25
	global_store_dwordx4 v[30:31], v[26:29], off offset:256
	v_mul_f32_e32 v22, 0x45800000, v32
	v_cndmask_b32_e32 v22, v32, v22, vcc
	v_mul_f32_e32 v20, v20, v22
	v_mul_f32_e32 v21, v21, v22
	v_mul_f32_e32 v18, v18, v22
	v_mul_f32_e32 v19, v19, v22
	v_mul_f32_e32 v16, v16, v22
	v_mul_f32_e32 v17, v17, v22
	s_and_b64 vcc, exec, s[38:39]
	v_mul_f32_e32 v14, v14, v22
	v_mul_f32_e32 v15, v15, v22
	s_cbranch_vccnz .LBB0_126
	v_mul_f32_e32 v23, 0xbfb8aa3b, v18
	v_exp_f32_e32 v23, v23
	s_nop 0
	v_add_f32_e32 v23, 1.0, v23
	v_rcp_f32_e32 v24, v23
	v_mul_f32_e32 v23, 0xbfb8aa3b, v14
	v_exp_f32_e32 v23, v23
	s_nop 0
	v_add_f32_e32 v23, 1.0, v23
	v_rcp_f32_e32 v26, v23
	v_mul_f32_e32 v23, 0xbfb8aa3b, v19
	v_exp_f32_e32 v23, v23
	s_nop 0
	v_add_f32_e32 v23, 1.0, v23
	v_rcp_f32_e32 v25, v23
	v_mul_f32_e32 v23, 0xbfb8aa3b, v15
	v_exp_f32_e32 v23, v23
	v_mul_f32_e32 v18, v18, v24
	v_mul_f32_e32 v19, v19, v25
	v_add_f32_e32 v23, 1.0, v23
	v_rcp_f32_e32 v27, v23
	v_mul_f32_e32 v23, 0xbfb8aa3b, v20
	v_exp_f32_e32 v23, v23
	v_mul_f32_e32 v14, v14, v26
	v_mul_f32_e32 v15, v15, v27
	v_add_f32_e32 v23, 1.0, v23
	v_rcp_f32_e32 v28, v23
	v_mul_f32_e32 v23, 0xbfb8aa3b, v16
	v_exp_f32_e32 v23, v23
	s_nop 0
	v_add_f32_e32 v23, 1.0, v23
	v_rcp_f32_e32 v30, v23
	v_mul_f32_e32 v23, 0xbfb8aa3b, v21
	v_exp_f32_e32 v23, v23
	s_nop 0
	v_add_f32_e32 v23, 1.0, v23
	v_rcp_f32_e32 v29, v23
	v_mul_f32_e32 v23, 0xbfb8aa3b, v17
	v_exp_f32_e32 v23, v23
	v_mul_f32_e32 v20, v20, v28
	v_mul_f32_e32 v21, v21, v29
	v_add_f32_e32 v23, 1.0, v23
	v_rcp_f32_e32 v31, v23
	s_nop 0
	v_mul_f32_e32 v16, v16, v30
	v_mul_f32_e32 v17, v17, v31
.LBB0_126:
	v_add_u32_e32 v24, 0xb0, v144
	v_cvt_pk_bf16_f32 v18, v18, v19
	v_cvt_pk_bf16_f32 v19, v20, v21
	v_cvt_pk_bf16_f32 v20, v14, v15
	v_mov_b64_e32 v[14:15], s[86:87]
	v_mov_b32_e32 v23, v22
	v_cvt_pk_bf16_f32 v21, v16, v17
	v_mad_i64_i32 v[14:15], s[10:11], v24, s55, v[14:15]
	v_mov_b32_e32 v16, v22
	v_mov_b32_e32 v17, v22
	v_lshl_add_u64 v[14:15], v[126:127], 1, v[14:15]
	v_mul_f32_e32 v12, v12, v16
	v_mul_f32_e32 v13, v13, v17
	v_mul_f32_e32 v10, v10, v22
	v_mul_f32_e32 v11, v11, v23
	v_mul_f32_e32 v8, v8, v16
	v_mul_f32_e32 v9, v9, v17
	s_and_b64 vcc, exec, s[38:39]
	v_mul_f32_e32 v6, v6, v22
	v_mul_f32_e32 v7, v7, v23
	global_store_dwordx4 v[14:15], v[18:21], off
	s_cbranch_vccnz .LBB0_128
	v_mul_f32_e32 v17, 0xbfb8aa3b, v6
	v_exp_f32_e32 v17, v17
	v_mul_f32_e32 v16, 0xbfb8aa3b, v10
	v_exp_f32_e32 v16, v16
	v_mul_f32_e32 v21, 0xbfb8aa3b, v8
	v_add_f32_e32 v17, 1.0, v17
	v_rcp_f32_e32 v18, v17
	v_mul_f32_e32 v17, 0xbfb8aa3b, v11
	v_exp_f32_e32 v17, v17
	v_add_f32_e32 v16, 1.0, v16
	v_exp_f32_e32 v21, v21
	v_rcp_f32_e32 v16, v16
	v_add_f32_e32 v17, 1.0, v17
	v_rcp_f32_e32 v17, v17
	v_add_f32_e32 v21, 1.0, v21
	v_mul_f32_e32 v19, 0xbfb8aa3b, v7
	v_mul_f32_e32 v20, 0xbfb8aa3b, v12
	v_rcp_f32_e32 v22, v21
	v_mul_f32_e32 v21, 0xbfb8aa3b, v13
	v_mul_f32_e32 v10, v10, v16
	v_mul_f32_e32 v11, v11, v17
	v_mul_f32_e32 v16, 0xbfb8aa3b, v9
	v_exp_f32_e32 v19, v19
	v_exp_f32_e32 v20, v20
	v_exp_f32_e32 v21, v21
	v_exp_f32_e32 v16, v16
	v_add_f32_e32 v19, 1.0, v19
	v_add_f32_e32 v20, 1.0, v20
	v_add_f32_e32 v21, 1.0, v21
	v_add_f32_e32 v16, 1.0, v16
	v_rcp_f32_e32 v19, v19
	v_rcp_f32_e32 v20, v20
	v_rcp_f32_e32 v21, v21
	v_rcp_f32_e32 v23, v16
	v_mul_f32_e32 v6, v6, v18
	v_mul_f32_e32 v7, v7, v19
	v_mul_f32_e32 v12, v12, v20
	v_mul_f32_e32 v13, v13, v21
	v_mul_f32_e32 v8, v8, v22
	v_mul_f32_e32 v9, v9, v23

; __device__ __forceinline__ unsigned cvtpk(float lo, float hi) { const f32x2v v = {lo, hi}; return __builtin_bit_cast(unsigned, __builtin_convertvector(v, bf16x2v)); }
; __device__ __forceinline__ void srg_phase(LAS unsigned char* L, const bf16* Aop, const bf16* Bt, const int K, bf16* xb, float* rowss, const float scale, const bool fin, const int G, const int tid) {
;     ...
;         {
;             const int row = MP + 64 * tm + 16 * wm + r16, col0 = 64 * tn + 32 * wn + 4 * q;
;             bf16* px = xb + (size_t)row * D + col0;
;             const v2u xa = *(const v2u*)px, xc = *(const v2u*)(px + 16);
;             const float a0 = __builtin_bit_cast(float, xa.x << 16) + acc0[0] * scale, a1 = __builtin_bit_cast(float, xa.x & 0xffff0000u) + acc0[1] * scale, a2 = __builtin_bit_cast(float, xa.y << 16) + acc0[2] * scale, a3 = __builtin_bit_cast(float, xa.y & 0xffff0000u) + acc0[3] * scale;
;             const float b0 = __builtin_bit_cast(float, xc.x << 16) + acc1[0] * scale, b1 = __builtin_bit_cast(float, xc.x & 0xffff0000u) + acc1[1] * scale, b2 = __builtin_bit_cast(float, xc.y << 16) + acc1[2] * scale, b3 = __builtin_bit_cast(float, xc.y & 0xffff0000u) + acc1[3] * scale;
;             v2u wa, wb; wa.x = cvtpk(a0, a1); wa.y = cvtpk(a2, a3); wb.x = cvtpk(b0, b1); wb.y = cvtpk(b2, b3);
;             *(v2u*)px = wa; *(v2u*)(px + 16) = wb;
;             float ss = 0.f;
; #pragma unroll
;             for (int k = 0; k < 2; ++k) { const unsigned pa = wa[k], pb = wb[k]; const float r0 = __builtin_bit_cast(float, pa << 16), r1 = __builtin_bit_cast(float, pa & 0xffff0000u), r2 = __builtin_bit_cast(float, pb << 16), r3 = __builtin_bit_cast(float, pb & 0xffff0000u); ss += (r0 * r0 + r1 * r1) + (r2 * r2 + r3 * r3); }
;             ss += __shfl_xor(ss, 16); ss += __shfl_xor(ss, 32);
;             if (q == 0 && fin) unsafeAtomicAdd(rowss + row, ss);
.Lsrg_exit_a:
	s_waitcnt vmcnt(4)
	v_add_u32_e32 v6, s0, v54
	v_ashrrev_i32_e32 v7, 31, v6
	v_or_b32_e32 v10, s1, v55
	v_lshlrev_b64 v[8:9], 11, v[6:7]
	v_lshl_add_u64 v[8:9], s[84:85], 0, v[8:9]
	v_lshlrev_b32_e32 v10, 1, v10
	v_mov_b32_e32 v11, v4
	v_lshl_add_u64 v[8:9], v[8:9], 0, v[10:11]
	global_load_dwordx2 v[10:11], v[8:9], off
	global_load_dwordx2 v[12:13], v[8:9], off offset:32
	s_waitcnt vmcnt(1)
	v_lshlrev_b32_e32 v14, 16, v10
	v_and_b32_e32 v15, 0xffff0000, v10
	v_lshlrev_b32_e32 v10, 16, v11
	v_and_b32_e32 v11, 0xffff0000, v11
	v_fma_f32 v14, v2, v38, v14
	v_fma_f32 v15, v3, v39, v15
	v_fma_f32 v10, v2, v40, v10
	v_fma_f32 v11, v3, v41, v11
	s_waitcnt vmcnt(0)
	v_lshlrev_b32_e32 v16, 16, v12
	v_and_b32_e32 v17, 0xffff0000, v12
	v_lshlrev_b32_e32 v12, 16, v13
	v_and_b32_e32 v13, 0xffff0000, v13
	v_fma_f32 v16, v2, v42, v16
	v_fma_f32 v17, v3, v43, v17
	v_fma_f32 v12, v2, v44, v12
	v_fma_f32 v13, v3, v45, v13
	v_cvt_pk_bf16_f32 v14, v14, v15
	v_cvt_pk_bf16_f32 v15, v10, v11
	v_cvt_pk_bf16_f32 v10, v16, v17
	v_cvt_pk_bf16_f32 v11, v12, v13
	global_store_dwordx2 v[8:9], v[14:15], off
	global_store_dwordx2 v[8:9], v[10:11], off offset:32
	v_and_b32_e32 v9, 0xffff0000, v14
	v_lshlrev_b32_e32 v8, 16, v14
	v_lshlrev_b32_e32 v12, 16, v10
	v_and_b32_e32 v10, 0xffff0000, v10
	v_mul_f32_e32 v9, v9, v9
	v_fmac_f32_e32 v9, v8, v8
	v_mul_f32_e32 v8, v10, v10
	v_fmac_f32_e32 v8, v12, v12
	v_and_b32_e32 v10, 0xffff0000, v15
	v_add_f32_e32 v8, v9, v8
	v_lshlrev_b32_e32 v9, 16, v15
	v_lshlrev_b32_e32 v12, 16, v11
	v_and_b32_e32 v11, 0xffff0000, v11
	v_mul_f32_e32 v10, v10, v10
	v_fmac_f32_e32 v10, v9, v9
	v_mul_f32_e32 v9, v11, v11
	v_fmac_f32_e32 v9, v12, v12
	v_add_f32_e32 v9, v10, v9
	v_and_b32_e32 v10, 64, v232
	v_add_f32_e32 v8, v8, v9
	v_xor_b32_e32 v9, 16, v232
	v_add_u32_e32 v10, 64, v10
	v_cmp_lt_i32_e32 vcc, v9, v10
	s_nop 1
	v_cndmask_b32_e32 v9, v232, v9, vcc
	v_lshlrev_b32_e32 v9, 2, v9
	ds_bpermute_b32 v9, v9, v8
	s_waitcnt lgkmcnt(0)
	v_add_f32_e32 v8, v8, v9
	v_xor_b32_e32 v9, 32, v232
	v_cmp_lt_i32_e32 vcc, v9, v10
	s_nop 1
	v_cndmask_b32_e32 v9, v232, v9, vcc
	v_lshlrev_b32_e32 v9, 2, v9
	ds_bpermute_b32 v9, v9, v8
	s_and_saveexec_b64 s[0:1], s[38:39]
	s_cbranch_execz .LBB0_137
	s_waitcnt lgkmcnt(0)
	v_add_f32_e32 v8, v8, v9
	v_lshl_add_u64 v[6:7], v[6:7], 2, s[8:9]
	global_atomic_add_f32 v[6:7], v8, off
	s_branch .LBB0_137

; __device__ __forceinline__ unsigned cvtpk(float lo, float hi) { const f32x2v v = {lo, hi}; return __builtin_bit_cast(unsigned, __builtin_convertvector(v, bf16x2v)); }
; __device__ __forceinline__ void srg_phase(LAS unsigned char* L, const bf16* Aop, const bf16* Bt, const int K, bf16* xb, float* rowss, const float scale, const bool fin, const int G, const int tid) {
;     ...
;         {
;             const int row = MP + 64 * tm + 16 * wm + r16, col0 = 64 * tn + 32 * wn + 4 * q;
;             bf16* px = xb + (size_t)row * D + col0;
;             const v2u xa = *(const v2u*)px, xc = *(const v2u*)(px + 16);
;             const float a0 = __builtin_bit_cast(float, xa.x << 16) + acc0[0] * scale, a1 = __builtin_bit_cast(float, xa.x & 0xffff0000u) + acc0[1] * scale, a2 = __builtin_bit_cast(float, xa.y << 16) + acc0[2] * scale, a3 = __builtin_bit_cast(float, xa.y & 0xffff0000u) + acc0[3] * scale;
;             const float b0 = __builtin_bit_cast(float, xc.x << 16) + acc1[0] * scale, b1 = __builtin_bit_cast(float, xc.x & 0xffff0000u) + acc1[1] * scale, b2 = __builtin_bit_cast(float, xc.y << 16) + acc1[2] * scale, b3 = __builtin_bit_cast(float, xc.y & 0xffff0000u) + acc1[3] * scale;
;             v2u wa, wb; wa.x = cvtpk(a0, a1); wa.y = cvtpk(a2, a3); wb.x = cvtpk(b0, b1); wb.y = cvtpk(b2, b3);
;             *(v2u*)px = wa; *(v2u*)(px + 16) = wb;
;             float ss = 0.f;
; #pragma unroll
;             for (int k = 0; k < 2; ++k) { const unsigned pa = wa[k], pb = wb[k]; const float r0 = __builtin_bit_cast(float, pa << 16), r1 = __builtin_bit_cast(float, pa & 0xffff0000u), r2 = __builtin_bit_cast(float, pb << 16), r3 = __builtin_bit_cast(float, pb & 0xffff0000u); ss += (r0 * r0 + r1 * r1) + (r2 * r2 + r3 * r3); }
;             ss += __shfl_xor(ss, 16); ss += __shfl_xor(ss, 32);
;             if (q == 0 && fin) unsafeAtomicAdd(rowss + row, ss);
.Lsrg_exit_b:
	s_waitcnt vmcnt(4)
	v_add_u32_e32 v6, s0, v55
	v_ashrrev_i32_e32 v7, 31, v6
	v_or_b32_e32 v10, s1, v56
	v_lshlrev_b64 v[8:9], 11, v[6:7]
	v_lshl_add_u64 v[8:9], s[84:85], 0, v[8:9]
	v_lshlrev_b32_e32 v10, 1, v10
	v_mov_b32_e32 v11, v4
	v_lshl_add_u64 v[8:9], v[8:9], 0, v[10:11]
	global_load_dwordx2 v[10:11], v[8:9], off
	global_load_dwordx2 v[12:13], v[8:9], off offset:32
	s_waitcnt vmcnt(1)
	v_lshlrev_b32_e32 v14, 16, v10
	v_and_b32_e32 v15, 0xffff0000, v10
	v_lshlrev_b32_e32 v10, 16, v11
	v_and_b32_e32 v11, 0xffff0000, v11
	v_fma_f32 v14, v2, v38, v14
	v_fma_f32 v15, v3, v39, v15
	v_fma_f32 v10, v2, v40, v10
	v_fma_f32 v11, v3, v41, v11
	s_waitcnt vmcnt(0)
	v_lshlrev_b32_e32 v16, 16, v12
	v_and_b32_e32 v17, 0xffff0000, v12
	v_lshlrev_b32_e32 v12, 16, v13
	v_and_b32_e32 v13, 0xffff0000, v13
	v_fma_f32 v16, v2, v42, v16
	v_fma_f32 v17, v3, v43, v17
	v_fma_f32 v12, v2, v44, v12
	v_fma_f32 v13, v3, v45, v13
	v_cvt_pk_bf16_f32 v14, v14, v15
	v_cvt_pk_bf16_f32 v15, v10, v11
	v_cvt_pk_bf16_f32 v10, v16, v17
	v_cvt_pk_bf16_f32 v11, v12, v13
	global_store_dwordx2 v[8:9], v[14:15], off
	global_store_dwordx2 v[8:9], v[10:11], off offset:32
	v_and_b32_e32 v9, 0xffff0000, v14
	v_lshlrev_b32_e32 v8, 16, v14
	v_lshlrev_b32_e32 v12, 16, v10
	v_and_b32_e32 v10, 0xffff0000, v10
	v_mul_f32_e32 v9, v9, v9
	v_fmac_f32_e32 v9, v8, v8
	v_mul_f32_e32 v8, v10, v10
	v_fmac_f32_e32 v8, v12, v12
	v_and_b32_e32 v10, 0xffff0000, v15
	v_add_f32_e32 v8, v9, v8
	v_lshlrev_b32_e32 v9, 16, v15
	v_lshlrev_b32_e32 v12, 16, v11
	v_and_b32_e32 v11, 0xffff0000, v11
	v_mul_f32_e32 v10, v10, v10
	v_fmac_f32_e32 v10, v9, v9
	v_mul_f32_e32 v9, v11, v11
	v_fmac_f32_e32 v9, v12, v12
	v_add_f32_e32 v9, v10, v9
	v_and_b32_e32 v10, 64, v232
	v_add_f32_e32 v8, v8, v9
	v_xor_b32_e32 v9, 16, v232
	v_add_u32_e32 v10, 64, v10
	v_cmp_lt_i32_e32 vcc, v9, v10
	s_nop 1
	v_cndmask_b32_e32 v9, v232, v9, vcc
	v_lshlrev_b32_e32 v9, 2, v9
	ds_bpermute_b32 v9, v9, v8
	s_waitcnt lgkmcnt(0)
	v_add_f32_e32 v8, v8, v9
	v_xor_b32_e32 v9, 32, v232
	v_cmp_lt_i32_e32 vcc, v9, v10
	s_nop 1
	v_cndmask_b32_e32 v9, v232, v9, vcc
	v_lshlrev_b32_e32 v9, 2, v9
	ds_bpermute_b32 v9, v9, v8
	s_and_saveexec_b64 s[0:1], s[36:37]
	s_cbranch_execz .LBB0_191
	s_waitcnt lgkmcnt(0)
	v_add_f32_e32 v8, v8, v9
	v_lshl_add_u64 v[6:7], v[6:7], 2, s[8:9]
	global_atomic_add_f32 v[6:7], v8, off
	s_branch .LBB0_191
